# v044_fnorm
# baseline (speedup 1.0000x reference)
.LBB0_633:
	s_or_b64 exec, exec, s[2:3]
	v_lshl_add_u64 v[30:31], s[48:49], 0, v[18:19]
	v_add_co_u32_e32 v42, vcc, s14, v30
	s_waitcnt vmcnt(0)
	ds_bpermute_b32 v29, v20, v28
	v_addc_co_u32_e32 v43, vcc, 0, v31, vcc
	global_load_dwordx4 v[30:33], v[42:43], off
	global_load_dwordx4 v[34:37], v[2:3], off
	global_load_dwordx4 v[38:41], v[2:3], off offset:16
	global_load_dwordx4 v[60:63], v[42:43], off offset:1024
	global_load_dwordx4 v[64:67], v[6:7], off
	global_load_dwordx4 v[68:71], v[6:7], off offset:16
	global_load_dwordx4 v[72:75], v[42:43], off offset:2048
	global_load_dwordx4 v[76:79], v[10:11], off
	global_load_dwordx4 v[80:83], v[10:11], off offset:16
	global_load_dwordx4 v[84:87], v[42:43], off offset:3072
	global_load_dwordx4 v[88:91], v[14:15], off
	global_load_dwordx4 v[92:95], v[14:15], off offset:16
	s_waitcnt lgkmcnt(0)
	v_add_f32_e32 v28, v28, v29
	ds_bpermute_b32 v29, v21, v28
	s_add_i32 s4, s4, s18
	v_lshl_add_u64 v[16:17], v[16:17], 0, s[6:7]
	v_lshl_add_u64 v[18:19], v[18:19], 0, s[8:9]
	s_waitcnt lgkmcnt(0)
	v_add_f32_e32 v28, v28, v29
	ds_bpermute_b32 v29, v22, v28
	s_waitcnt lgkmcnt(0)
	v_add_f32_e32 v28, v28, v29
	ds_bpermute_b32 v29, v23, v28
	s_waitcnt lgkmcnt(0)
	v_add_f32_e32 v28, v28, v29
	ds_bpermute_b32 v29, v24, v28
	s_waitcnt lgkmcnt(0)
	v_add_f32_e32 v28, v28, v29
	ds_bpermute_b32 v29, v25, v28
	s_waitcnt lgkmcnt(0)
	v_add_f32_e32 v28, v28, v29
	v_fmamk_f32 v28, v28, 0x3a000000, v26
	v_mul_f32_e32 v29, 0x4f800000, v28
	v_cmp_gt_f32_e32 vcc, s5, v28
	s_nop 1
	v_cndmask_b32_e32 v28, v28, v29, vcc
	v_sqrt_f32_e32 v29, v28
	s_nop 0
	v_add_u32_e32 v44, -1, v29
	v_add_u32_e32 v45, 1, v29
	v_fma_f32 v46, -v44, v29, v28
	v_fma_f32 v47, -v45, v29, v28
	v_cmp_ge_f32_e64 s[2:3], 0, v46
	s_nop 1
	v_cndmask_b32_e64 v29, v29, v44, s[2:3]
	v_cmp_lt_f32_e64 s[2:3], 0, v47
	s_nop 1
	v_cndmask_b32_e64 v29, v29, v45, s[2:3]
	v_mul_f32_e32 v44, 0x37800000, v29
	v_cndmask_b32_e32 v29, v29, v44, vcc
	v_cmp_class_f32_e32 vcc, v28, v27
	v_lshl_add_u64 v[44:45], s[10:11], 0, v[0:1]
	s_nop 0
	v_cndmask_b32_e32 v28, v29, v28, vcc
	v_div_scale_f32 v29, s[2:3], v28, v28, 1.0
	v_rcp_f32_e32 v46, v29
	v_div_scale_f32 v47, vcc, 1.0, v28, 1.0
	v_fma_f32 v48, -v29, v46, 1.0
	v_fmac_f32_e32 v46, v48, v46
	v_mul_f32_e32 v48, v47, v46
	v_fma_f32 v49, -v29, v48, v47
	v_fmac_f32_e32 v48, v49, v46
	v_fma_f32 v29, -v29, v48, v47
	v_div_fmas_f32 v29, v29, v46, v48
	v_div_fixup_f32 v46, v29, v28, 1.0
	s_waitcnt vmcnt(11)
	v_lshlrev_b32_e32 v28, 16, v30
	v_and_b32_e32 v29, 0xffff0000, v30
	v_lshlrev_b32_e32 v30, 16, v31
	v_and_b32_e32 v31, 0xffff0000, v31
	v_lshlrev_b32_e32 v48, 16, v32
	v_and_b32_e32 v49, 0xffff0000, v32
	v_lshlrev_b32_e32 v32, 16, v33
	v_and_b32_e32 v33, 0xffff0000, v33
	v_pk_mul_f32 v[28:29], v[46:47], v[28:29] op_sel_hi:[0,1]
	v_pk_mul_f32 v[30:31], v[46:47], v[30:31] op_sel_hi:[0,1]
	v_pk_mul_f32 v[48:49], v[46:47], v[48:49] op_sel_hi:[0,1]
	v_pk_mul_f32 v[32:33], v[46:47], v[32:33] op_sel_hi:[0,1]
	s_waitcnt vmcnt(10)
	v_pk_mul_f32 v[30:31], v[36:37], v[30:31]
	v_pk_mul_f32 v[28:29], v[34:35], v[28:29]
	s_waitcnt vmcnt(9)
	v_pk_mul_f32 v[34:35], v[40:41], v[32:33]
	v_pk_mul_f32 v[32:33], v[38:39], v[48:49]
	global_store_dwordx4 v[44:45], v[28:31], off
	global_store_dwordx4 v[44:45], v[32:35], off offset:16
	v_lshl_add_u64 v[40:41], s[10:11], 0, v[4:5]
	s_waitcnt vmcnt(10)
	v_mov_b32_e32 v28, v60
	v_mov_b32_e32 v29, v61
	v_mov_b32_e32 v30, v62
	v_mov_b32_e32 v31, v63
	v_lshlrev_b32_e32 v44, 16, v28
	v_and_b32_e32 v45, 0xffff0000, v28
	v_lshlrev_b32_e32 v28, 16, v29
	v_and_b32_e32 v29, 0xffff0000, v29
	v_lshlrev_b32_e32 v48, 16, v30
	v_and_b32_e32 v49, 0xffff0000, v30
	v_lshlrev_b32_e32 v30, 16, v31
	v_and_b32_e32 v31, 0xffff0000, v31
	v_pk_mul_f32 v[44:45], v[46:47], v[44:45] op_sel_hi:[0,1]
	v_pk_mul_f32 v[28:29], v[46:47], v[28:29] op_sel_hi:[0,1]
	v_pk_mul_f32 v[48:49], v[46:47], v[48:49] op_sel_hi:[0,1]
	v_pk_mul_f32 v[50:51], v[46:47], v[30:31] op_sel_hi:[0,1]
	s_waitcnt vmcnt(9)
	v_mov_b32_e32 v32, v64
	v_mov_b32_e32 v33, v65
	v_mov_b32_e32 v34, v66
	v_mov_b32_e32 v35, v67
	v_pk_mul_f32 v[30:31], v[34:35], v[28:29]
	v_pk_mul_f32 v[28:29], v[32:33], v[44:45]
	s_waitcnt vmcnt(8)
	v_mov_b32_e32 v36, v68
	v_mov_b32_e32 v37, v69
	v_mov_b32_e32 v38, v70
	v_mov_b32_e32 v39, v71
	v_pk_mul_f32 v[34:35], v[38:39], v[50:51]
	v_pk_mul_f32 v[32:33], v[36:37], v[48:49]
	global_store_dwordx4 v[40:41], v[28:31], off
	global_store_dwordx4 v[40:41], v[32:35], off offset:16
	v_lshl_add_u64 v[40:41], s[10:11], 0, v[8:9]
	s_waitcnt vmcnt(9)
	v_mov_b32_e32 v28, v72
	v_mov_b32_e32 v29, v73
	v_mov_b32_e32 v30, v74
	v_mov_b32_e32 v31, v75
	v_lshlrev_b32_e32 v44, 16, v28
	v_and_b32_e32 v45, 0xffff0000, v28
	v_lshlrev_b32_e32 v28, 16, v29
	v_and_b32_e32 v29, 0xffff0000, v29
	v_lshlrev_b32_e32 v48, 16, v30
	v_and_b32_e32 v49, 0xffff0000, v30
	v_lshlrev_b32_e32 v30, 16, v31
	v_and_b32_e32 v31, 0xffff0000, v31
	v_pk_mul_f32 v[44:45], v[46:47], v[44:45] op_sel_hi:[0,1]
	v_pk_mul_f32 v[28:29], v[46:47], v[28:29] op_sel_hi:[0,1]
	v_pk_mul_f32 v[48:49], v[46:47], v[48:49] op_sel_hi:[0,1]
	v_pk_mul_f32 v[50:51], v[46:47], v[30:31] op_sel_hi:[0,1]
	s_waitcnt vmcnt(8)
	v_mov_b32_e32 v32, v76
	v_mov_b32_e32 v33, v77
	v_mov_b32_e32 v34, v78
	v_mov_b32_e32 v35, v79
	v_pk_mul_f32 v[30:31], v[34:35], v[28:29]
	v_pk_mul_f32 v[28:29], v[32:33], v[44:45]
	s_waitcnt vmcnt(7)
	v_mov_b32_e32 v36, v80
	v_mov_b32_e32 v37, v81
	v_mov_b32_e32 v38, v82
	v_mov_b32_e32 v39, v83
	v_pk_mul_f32 v[34:35], v[38:39], v[50:51]
	v_pk_mul_f32 v[32:33], v[36:37], v[48:49]
	global_store_dwordx4 v[40:41], v[28:31], off offset:-16
	global_store_dwordx4 v[40:41], v[32:35], off
	v_lshl_add_u64 v[40:41], s[10:11], 0, v[12:13]
	s_add_u32 s10, s10, s12
	s_addc_u32 s11, s11, s13
	s_cmpk_lt_i32 s4, 0x6000
	s_waitcnt vmcnt(8)
	v_mov_b32_e32 v28, v84
	v_mov_b32_e32 v29, v85
	v_mov_b32_e32 v30, v86
	v_mov_b32_e32 v31, v87
	v_lshlrev_b32_e32 v42, 16, v28
	v_and_b32_e32 v43, 0xffff0000, v28
	v_lshlrev_b32_e32 v28, 16, v29
	v_and_b32_e32 v29, 0xffff0000, v29
	v_lshlrev_b32_e32 v44, 16, v30
	v_and_b32_e32 v45, 0xffff0000, v30
	v_lshlrev_b32_e32 v30, 16, v31
	v_and_b32_e32 v31, 0xffff0000, v31
	v_pk_mul_f32 v[42:43], v[46:47], v[42:43] op_sel_hi:[0,1]
	v_pk_mul_f32 v[28:29], v[46:47], v[28:29] op_sel_hi:[0,1]
	v_pk_mul_f32 v[44:45], v[46:47], v[44:45] op_sel_hi:[0,1]
	v_pk_mul_f32 v[46:47], v[46:47], v[30:31] op_sel_hi:[0,1]
	s_waitcnt vmcnt(7)
	v_mov_b32_e32 v32, v88
	v_mov_b32_e32 v33, v89
	v_mov_b32_e32 v34, v90
	v_mov_b32_e32 v35, v91
	v_pk_mul_f32 v[30:31], v[34:35], v[28:29]
	v_pk_mul_f32 v[28:29], v[32:33], v[42:43]
	s_waitcnt vmcnt(6)
	v_mov_b32_e32 v36, v92
	v_mov_b32_e32 v37, v93
	v_mov_b32_e32 v38, v94
	v_mov_b32_e32 v39, v95
	v_pk_mul_f32 v[34:35], v[38:39], v[46:47]
	v_pk_mul_f32 v[32:33], v[36:37], v[44:45]
	global_store_dwordx4 v[40:41], v[28:31], off offset:-16
	global_store_dwordx4 v[40:41], v[32:35], off
	s_cbranch_scc0 .LBB0_636
